# A-merge loop: group-output row loads issued together with the LSE loads (one round trip per item)
# speedup vs baseline: 1.0147x; 1.0034x over previous
; __device__ __forceinline__ unsigned pk2(float lo, float hi) { return f2bf(lo) | (f2bf(hi) << 16); }
; __device__ __forceinline__ void mixA_merge(const bf16* Z, const float* LSE, bf16* Ya, int gtid, int gthreads) {
;     for (int it = gtid; it < MC * 64; it += gthreads) {
;         const int tok = it >> 6, h = (it >> 3) & 7, ch = it & 7;
;         const float l0 = LSE[((size_t)0 * MC + tok) * 8 + h], l1 = LSE[((size_t)1 * MC + tok) * 8 + h], l2 = LSE[((size_t)2 * MC + tok) * 8 + h];
;         const float mx = fmaxf(l0, fmaxf(l1, l2));
;         float w0 = __expf(l0 - mx), w1 = __expf(l1 - mx), w2 = __expf(l2 - mx); const float inv = 1.f / (w0 + w1 + w2); w0 *= inv; w1 *= inv; w2 *= inv;
;         const bf16* zp = Z + (size_t)tok * NZ + h * 64 + ch * 8;
;         float a[8], b[8], c[8]; unpack8(*(const uint4*)zp, a); unpack8(*(const uint4*)(zp + 512), b); unpack8(*(const uint4*)(zp + 1024), c);
;         uint4 wv; wv.x = pk2(w0 * a[0] + w1 * b[0] + w2 * c[0], w0 * a[1] + w1 * b[1] + w2 * c[1]); wv.y = pk2(w0 * a[2] + w1 * b[2] + w2 * c[2], w0 * a[3] + w1 * b[3] + w2 * c[3]);
;         wv.z = pk2(w0 * a[4] + w1 * b[4] + w2 * c[4], w0 * a[5] + w1 * b[5] + w2 * c[5]); wv.w = pk2(w0 * a[6] + w1 * b[6] + w2 * c[6], w0 * a[7] + w1 * b[7] + w2 * c[7]);
;         *(uint4*)(Ya + (size_t)tok * 512 + h * 64 + ch * 8) = wv;
;     }
.LBB0_157:
	v_ashrrev_i32_e32 v4, 6, v2
	v_ashrrev_i32_e32 v5, 31, v4
	v_bfe_u32 v3, v2, 3, 3
	v_lshlrev_b64 v[6:7], 5, v[4:5]
	v_lshl_add_u64 v[6:7], s[16:17], 0, v[6:7]
	v_lshlrev_b32_e32 v8, 2, v3
	v_mov_b32_e32 v9, v0
	v_lshl_add_u64 v[6:7], v[6:7], 0, v[8:9]
	v_add_co_u32_e32 v8, vcc, 0x80000, v6
	global_load_dword v10, v[6:7], off
	s_nop 0
	v_addc_co_u32_e32 v9, vcc, 0, v7, vcc
	global_load_dword v8, v[8:9], off
	v_add_co_u32_e32 v6, vcc, s22, v6
	v_mov_b32_e32 v15, v0
	s_nop 0
	v_addc_co_u32_e32 v7, vcc, 0, v7, vcc
	global_load_dword v9, v[6:7], off
	v_mov_b64_e32 v[44:45], s[12:13]
	v_mad_i64_i32 v[44:45], s[2:3], v4, s66, v[44:45]
	v_lshlrev_b32_e32 v46, 7, v3
	v_mov_b32_e32 v47, v0
	v_and_b32_e32 v3, 56, v1
	v_lshlrev_b64 v[4:5], 10, v[4:5]
	v_lshl_add_u64 v[44:45], v[44:45], 0, v[46:47]
	v_lshlrev_b32_e32 v14, 1, v3
	v_lshl_add_u64 v[4:5], s[14:15], 0, v[4:5]
	v_lshl_add_u64 v[18:19], v[44:45], 0, v[14:15]
	v_lshl_add_u64 v[4:5], v[4:5], 0, v[46:47]
	v_lshl_add_u64 v[20:21], v[4:5], 0, v[14:15]
	global_load_dwordx4 v[32:35], v[18:19], off
	global_load_dwordx4 v[36:39], v[18:19], off offset:1024
	global_load_dwordx4 v[40:43], v[18:19], off offset:2048
	v_add_u32_e32 v2, s24, v2
	s_waitcnt vmcnt(3)
	v_max3_f32 v11, v10, v8, v9
	v_sub_f32_e32 v6, v10, v11
	v_mul_f32_e32 v6, 0x3fb8aa3b, v6
	v_exp_f32_e32 v7, v6
	v_sub_f32_e32 v6, v8, v11
	v_mul_f32_e32 v6, 0x3fb8aa3b, v6
	v_sub_f32_e32 v8, v9, v11
	v_exp_f32_e32 v6, v6
	v_mul_f32_e32 v8, 0x3fb8aa3b, v8
	v_exp_f32_e32 v9, v8
	v_add_f32_e32 v8, v7, v6
	v_add_f32_e32 v8, v9, v8
	v_div_scale_f32 v10, s[2:3], v8, v8, 1.0
	v_rcp_f32_e32 v11, v10
	s_nop 0
	v_fma_f32 v12, -v10, v11, 1.0
	v_fmac_f32_e32 v11, v12, v11
	v_div_scale_f32 v12, vcc, 1.0, v8, 1.0
	v_mul_f32_e32 v13, v12, v11
	v_fma_f32 v14, -v10, v13, v12
	v_fmac_f32_e32 v13, v14, v11
	v_fma_f32 v10, -v10, v13, v12
	v_div_fmas_f32 v10, v10, v11, v13
	v_div_fixup_f32 v8, v10, v8, 1.0
	v_mul_f32_e32 v16, v9, v8
	v_pk_mul_f32 v[22:23], v[6:7], v[8:9] op_sel_hi:[1,0]
	s_mov_b32 s2, 0xfffff
	v_cmp_lt_i32_e32 vcc, s2, v2
	v_add_u32_e32 v1, s37, v1
	s_or_b64 s[40:41], vcc, s[40:41]
	s_waitcnt vmcnt(2)
	v_lshlrev_b32_e32 v28, 16, v32
	s_waitcnt vmcnt(1)
	v_lshlrev_b32_e32 v29, 16, v37
	v_lshlrev_b32_e32 v25, 16, v33
	v_lshlrev_b32_e32 v24, 16, v36
	v_and_b32_e32 v27, 0xffff0000, v33
	v_and_b32_e32 v33, 0xffff0000, v37
	v_and_b32_e32 v32, 0xffff0000, v32
	v_pk_mul_f32 v[18:19], v[22:23], v[28:29] op_sel:[1,0] op_sel_hi:[0,1]
	v_and_b32_e32 v26, 0xffff0000, v36
	s_waitcnt vmcnt(0)
	v_lshlrev_b32_e32 v37, 16, v41
	v_lshlrev_b32_e32 v36, 16, v40
	v_pk_fma_f32 v[18:19], v[22:23], v[24:25], v[18:19]
	v_pk_mul_f32 v[32:33], v[22:23], v[32:33] op_sel:[1,0] op_sel_hi:[0,1]
	v_and_b32_e32 v41, 0xffff0000, v41
	v_and_b32_e32 v40, 0xffff0000, v40
	v_pk_fma_f32 v[36:37], v[16:17], v[36:37], v[18:19] op_sel_hi:[0,1,1]
	v_pk_fma_f32 v[32:33], v[22:23], v[26:27], v[32:33]
	v_and_b32_sdwa v3, v37, v228 dst_sel:DWORD dst_unused:UNUSED_PAD src0_sel:WORD_1 src1_sel:DWORD
	v_pk_fma_f32 v[32:33], v[16:17], v[40:41], v[32:33] op_sel_hi:[0,1,1]
	v_and_b32_sdwa v40, v36, v228 dst_sel:DWORD dst_unused:UNUSED_PAD src0_sel:WORD_1 src1_sel:DWORD
	v_add3_u32 v36, v36, v40, s4
	v_and_b32_sdwa v40, v32, v228 dst_sel:DWORD dst_unused:UNUSED_PAD src0_sel:WORD_1 src1_sel:DWORD
	v_add3_u32 v32, v32, v40, s4
	v_add3_u32 v3, v37, v3, s4
	v_and_b32_sdwa v37, v33, v228 dst_sel:DWORD dst_unused:UNUSED_PAD src0_sel:WORD_1 src1_sel:DWORD
	v_and_b32_e32 v32, 0xffff0000, v32
	v_lshlrev_b32_e32 v19, 16, v39
	v_lshlrev_b32_e32 v18, 16, v34
	v_add3_u32 v33, v33, v37, s4
	v_or_b32_sdwa v32, v32, v36 dst_sel:DWORD dst_unused:UNUSED_PAD src0_sel:DWORD src1_sel:WORD_1
	v_lshlrev_b32_e32 v37, 16, v35
	v_lshlrev_b32_e32 v36, 16, v38
	v_and_b32_e32 v41, 0xffff0000, v35
	v_and_b32_e32 v35, 0xffff0000, v39
	v_and_b32_e32 v34, 0xffff0000, v34
	v_pk_mul_f32 v[18:19], v[22:23], v[18:19] op_sel:[1,0] op_sel_hi:[0,1]
	v_and_b32_e32 v40, 0xffff0000, v38
	v_lshlrev_b32_e32 v39, 16, v43
	v_lshlrev_b32_e32 v38, 16, v42
	v_pk_fma_f32 v[36:37], v[22:23], v[36:37], v[18:19]
	v_pk_mul_f32 v[34:35], v[22:23], v[34:35] op_sel:[1,0] op_sel_hi:[0,1]
	v_and_b32_e32 v33, 0xffff0000, v33
	v_and_b32_e32 v43, 0xffff0000, v43
	v_and_b32_e32 v42, 0xffff0000, v42
	v_pk_fma_f32 v[36:37], v[16:17], v[38:39], v[36:37] op_sel_hi:[0,1,1]
	v_pk_fma_f32 v[34:35], v[22:23], v[40:41], v[34:35]
	v_or_b32_sdwa v33, v33, v3 dst_sel:DWORD dst_unused:UNUSED_PAD src0_sel:DWORD src1_sel:WORD_1
	v_pk_fma_f32 v[34:35], v[16:17], v[42:43], v[34:35] op_sel_hi:[0,1,1]
	v_and_b32_sdwa v3, v37, v228 dst_sel:DWORD dst_unused:UNUSED_PAD src0_sel:WORD_1 src1_sel:DWORD
	v_and_b32_sdwa v38, v36, v228 dst_sel:DWORD dst_unused:UNUSED_PAD src0_sel:WORD_1 src1_sel:DWORD
	v_add3_u32 v36, v36, v38, s4
	v_add3_u32 v3, v37, v3, s4
	v_and_b32_sdwa v37, v35, v228 dst_sel:DWORD dst_unused:UNUSED_PAD src0_sel:WORD_1 src1_sel:DWORD
	v_and_b32_sdwa v38, v34, v228 dst_sel:DWORD dst_unused:UNUSED_PAD src0_sel:WORD_1 src1_sel:DWORD
	v_add3_u32 v35, v35, v37, s4
	v_add3_u32 v34, v34, v38, s4
	v_and_b32_e32 v35, 0xffff0000, v35
	v_and_b32_e32 v34, 0xffff0000, v34
	v_or_b32_sdwa v35, v35, v3 dst_sel:DWORD dst_unused:UNUSED_PAD src0_sel:DWORD src1_sel:WORD_1
	v_or_b32_sdwa v34, v34, v36 dst_sel:DWORD dst_unused:UNUSED_PAD src0_sel:DWORD src1_sel:WORD_1
	global_store_dwordx4 v[20:21], v[32:35], off
	s_andn2_b64 exec, exec, s[40:41]
	s_cbranch_execnz .LBB0_157
